# rwkv lora block rescheduled + early prefetch; s5post and gaterw inner loops: weight loads issued together with counted waits
# speedup vs baseline: 1.3803x; 1.3803x over previous
; __device__ __forceinline__ float sigmoidf_(float x) { return rcpf_(1.f + __expf(-x)); }
; #define CK_MFMA(a, b, c) __builtin_amdgcn_mfma_f32_16x16x32_bf16(a, b, c, 0, 0, 0)
; __device__ __forceinline__ void rwkv_job(const PP& p, int l, int job, float* sm) {
;     ...
;         auto loadm = [&](int blk) {
;             if (blk < NCH) {
;                 const int jm = seqpos(dir, blk * 32 + mt * 16 + fr);
;                 const bf16_t* mp = RWP + (size_t)(b * TT + jm) * RWP_LD + 768 + fq * 8;
;                 xw[0] = *(const bf16x8*)mp; xw[1] = *(const bf16x8*)(mp + 32); xa[0] = *(const bf16x8*)(mp + 64); xa[1] = *(const bf16x8*)(mp + 96);
;             }
;         };
;         loadm(0);
;         auto lora = [&](int blk) {
;             if (blk >= NCH) return;
;             float* sWb = sW + (blk & 1) * ck::SWBUF; float* sAb = sAA + (blk & 1) * ck::SWBUF;
; #pragma unroll
;             for (int nt = 0; nt < 4; ++nt) {
;                 f32x4 aw = (f32x4){0.f, 0.f, 0.f, 0.f}, aa = aw;
; #pragma unroll
;                 for (int ks = 0; ks < 2; ++ks) { aw = CK_MFMA(xw[ks], wfw[nt][ks], aw); aa = CK_MFMA(xa[ks], wfa[nt][ks], aa); }
;                 const float w0s = cst[256 + nt * 16 + fr], a0s = cst[320 + nt * 16 + fr];
;                 f32x4 G = (f32x4){0.f, 0.f, 0.f, 0.f};
; #pragma unroll
;                 for (int i = 0; i < 4; ++i) {
;                     const float lw = -0.6065306597126334f * sigmoidf_(aw[i] + w0s);
;                     G = __builtin_amdgcn_mfma_f32_16x16x4f32((4 * fq + i <= fr) ? 1.f : 0.f, lw, G, 0, 0, 0);
;                 }
; #pragma unroll
;                 for (int i = 0; i < 4; ++i) {
;                     sWb[(mt * 16 + 4 * fq + i) * ck::SWLD + nt * 16 + fr] = G[i];
;                     sAb[(mt * 16 + 4 * fq + i) * ck::SWLD + nt * 16 + fr] = sigmoidf_(aa[i] + a0s);
;                 }
;             }
;             loadm(blk + 1);
;         };
.LBB0_688:
	s_waitcnt lgkmcnt(0)
	s_barrier
	s_cmpk_gt_u32 s22, 0x105
	s_cbranch_scc1 .LBB0_685
	s_waitcnt vmcnt(0)
	s_mov_b32 s98, 0xbfb8aa3b
	ds_read_b32 v122, v102 offset:1024
	ds_read_b32 v123, v102 offset:1088
	ds_read_b32 v124, v102 offset:1152
	ds_read_b32 v125, v102 offset:1216
	ds_read_b32 v126, v102 offset:1280
	ds_read_b32 v127, v102 offset:1344
	ds_read_b32 v158, v102 offset:1408
	ds_read_b32 v159, v102 offset:1472
	s_bitcmp1_b32 s22, 0
	s_cselect_b32 s4, 0x2200, 0
	s_add_i32 s5, s4, 0x1c800
	s_add_i32 s4, s4, 0x20c00
	v_mfma_f32_16x16x32_bf16 v[142:145], v[66:69], v[2:5], 0
	v_mfma_f32_16x16x32_bf16 v[146:149], v[66:69], v[18:21], 0
	v_mfma_f32_16x16x32_bf16 v[150:153], v[66:69], v[34:37], 0
	v_mfma_f32_16x16x32_bf16 v[154:157], v[66:69], v[50:53], 0
	v_mfma_f32_16x16x32_bf16 v[142:145], v[70:73], v[6:9], v[142:145]
	v_mfma_f32_16x16x32_bf16 v[146:149], v[70:73], v[22:25], v[146:149]
	v_mfma_f32_16x16x32_bf16 v[150:153], v[70:73], v[38:41], v[150:153]
	v_mfma_f32_16x16x32_bf16 v[154:157], v[70:73], v[54:57], v[154:157]
	v_mfma_f32_16x16x32_bf16 v[188:191], v[74:77], v[10:13], 0
	v_mfma_f32_16x16x32_bf16 v[192:195], v[74:77], v[26:29], 0
	v_mfma_f32_16x16x32_bf16 v[196:199], v[74:77], v[42:45], 0
	v_mfma_f32_16x16x32_bf16 v[200:203], v[74:77], v[58:61], 0
	v_mfma_f32_16x16x32_bf16 v[188:191], v[78:81], v[14:17], v[188:191]
	v_mfma_f32_16x16x32_bf16 v[192:195], v[78:81], v[30:33], v[192:195]
	v_mfma_f32_16x16x32_bf16 v[196:199], v[78:81], v[46:49], v[196:199]
	v_mfma_f32_16x16x32_bf16 v[200:203], v[78:81], v[62:65], v[200:203]
	s_cmpk_eq_i32 s7, 0x20a0
	s_cbranch_scc1 .Lrw_lora_noload
	s_and_b64 vcc, exec, s[34:35]
	s_cbranch_vccnz .Lrw_lora_fwd
	s_lshl_b32 s99, s22, 5
	v_add3_u32 v160, s99, 64, v116
	v_add_u32_e32 v161, s7, v118
	v_or_b32_e32 v160, v160, v1
	s_movk_i32 s99, 0xff
	v_cmp_lt_u32_e32 vcc, s99, v161
	v_sub_u32_e32 v161, 0xff, v160
	v_sub_u32_e32 v160, 0x21ff, v160
	s_nop 0
	v_cndmask_b32_e32 v160, v161, v160, vcc
	s_branch .Lrw_lora_addr
.Lrw_lora_fwd:
	v_add_u32_e32 v160, s7, v119
.Lrw_lora_addr:
	v_add_u32_e32 v160, s12, v160
	s_movk_i32 s99, 0x700
	v_mad_i64_i32 v[186:187], vcc, v160, s99, v[98:99]
	global_load_dwordx4 v[66:69], v[186:187], off offset:1536
	global_load_dwordx4 v[70:73], v[186:187], off offset:1600
	global_load_dwordx4 v[74:77], v[186:187], off offset:1664
	global_load_dwordx4 v[78:81], v[186:187], off offset:1728
.Lrw_lora_noload:
	s_waitcnt lgkmcnt(0)
	v_mul_f32_e32 v122, 0xbfb8aa3b, v122
	v_mul_f32_e32 v123, 0xbfb8aa3b, v123
	v_mul_f32_e32 v124, 0xbfb8aa3b, v124
	v_mul_f32_e32 v125, 0xbfb8aa3b, v125
	v_mul_f32_e32 v126, 0xbfb8aa3b, v126
	v_mul_f32_e32 v127, 0xbfb8aa3b, v127
	v_mul_f32_e32 v158, 0xbfb8aa3b, v158
	v_mul_f32_e32 v159, 0xbfb8aa3b, v159
	v_fma_f32 v142, v142, s98, v122
	v_fma_f32 v146, v146, s98, v123
	v_fma_f32 v150, v150, s98, v124
	v_fma_f32 v154, v154, s98, v125
	v_exp_f32_e32 v142, v142
	v_exp_f32_e32 v146, v146
	v_exp_f32_e32 v150, v150
	v_exp_f32_e32 v154, v154
	v_add_f32_e32 v142, 1.0, v142
	v_add_f32_e32 v146, 1.0, v146
	v_add_f32_e32 v150, 1.0, v150
	v_add_f32_e32 v154, 1.0, v154
	v_rcp_f32_e32 v142, v142
	v_rcp_f32_e32 v146, v146
	v_rcp_f32_e32 v150, v150
	v_rcp_f32_e32 v154, v154
	v_mul_f32_e32 v142, 0xbf1b4598, v142
	v_mul_f32_e32 v146, 0xbf1b4598, v146
	v_mul_f32_e32 v150, 0xbf1b4598, v150
	v_mul_f32_e32 v154, 0xbf1b4598, v154
	v_mfma_f32_16x16x4_f32 v[204:207], v103, v142, 0
	v_fma_f32 v143, v143, s98, v122
	v_fma_f32 v147, v147, s98, v123
	v_fma_f32 v151, v151, s98, v124
	v_fma_f32 v155, v155, s98, v125
	v_fma_f32 v188, v188, s98, v126
	v_fma_f32 v189, v189, s98, v126
	v_fma_f32 v190, v190, s98, v126
	v_fma_f32 v191, v191, s98, v126
	v_exp_f32_e32 v143, v143
	v_mfma_f32_16x16x4_f32 v[208:211], v103, v146, 0
	v_exp_f32_e32 v147, v147
	v_exp_f32_e32 v151, v151
	v_exp_f32_e32 v155, v155
	v_exp_f32_e32 v188, v188
	v_exp_f32_e32 v189, v189
	v_exp_f32_e32 v190, v190
	v_exp_f32_e32 v191, v191
	v_add_f32_e32 v143, 1.0, v143
	v_add_f32_e32 v147, 1.0, v147
	v_mfma_f32_16x16x4_f32 v[212:215], v103, v150, 0
	v_add_f32_e32 v151, 1.0, v151
	v_add_f32_e32 v155, 1.0, v155
	v_add_f32_e32 v188, 1.0, v188
	v_add_f32_e32 v189, 1.0, v189
	v_add_f32_e32 v190, 1.0, v190
	v_add_f32_e32 v191, 1.0, v191
	v_rcp_f32_e32 v143, v143
	v_rcp_f32_e32 v147, v147
	v_rcp_f32_e32 v151, v151
	v_mfma_f32_16x16x4_f32 v[182:185], v103, v154, 0
	v_rcp_f32_e32 v155, v155
	v_rcp_f32_e32 v188, v188
	v_rcp_f32_e32 v189, v189
	v_rcp_f32_e32 v190, v190
	v_rcp_f32_e32 v191, v191
	v_mul_f32_e32 v143, 0xbf1b4598, v143
	v_mul_f32_e32 v147, 0xbf1b4598, v147
	v_mul_f32_e32 v151, 0xbf1b4598, v151
	v_mul_f32_e32 v155, 0xbf1b4598, v155
	v_mfma_f32_16x16x4_f32 v[204:207], v104, v143, v[204:207]
	v_fma_f32 v144, v144, s98, v122
	v_fma_f32 v148, v148, s98, v123
	v_fma_f32 v152, v152, s98, v124
	v_fma_f32 v156, v156, s98, v125
; __device__ __forceinline__ float sigmoidf_(float x) { return rcpf_(1.f + __expf(-x)); }
; #define CK_MFMA(a, b, c) __builtin_amdgcn_mfma_f32_16x16x32_bf16(a, b, c, 0, 0, 0)
; __device__ __forceinline__ void rwkv_job(const PP& p, int l, int job, float* sm) {
;     ...
;         auto loadm = [&](int blk) {
;             if (blk < NCH) {
;                 const int jm = seqpos(dir, blk * 32 + mt * 16 + fr);
;                 const bf16_t* mp = RWP + (size_t)(b * TT + jm) * RWP_LD + 768 + fq * 8;
;                 xw[0] = *(const bf16x8*)mp; xw[1] = *(const bf16x8*)(mp + 32); xa[0] = *(const bf16x8*)(mp + 64); xa[1] = *(const bf16x8*)(mp + 96);
;             }
;     ...
;         auto lora = [&](int blk) {
;             if (blk >= NCH) return;
;             float* sWb = sW + (blk & 1) * ck::SWBUF; float* sAb = sAA + (blk & 1) * ck::SWBUF;
; #pragma unroll
;             for (int nt = 0; nt < 4; ++nt) {
;                 f32x4 aw = (f32x4){0.f, 0.f, 0.f, 0.f}, aa = aw;
; #pragma unroll
;                 for (int ks = 0; ks < 2; ++ks) { aw = CK_MFMA(xw[ks], wfw[nt][ks], aw); aa = CK_MFMA(xa[ks], wfa[nt][ks], aa); }
;                 const float w0s = cst[256 + nt * 16 + fr], a0s = cst[320 + nt * 16 + fr];
;                 f32x4 G = (f32x4){0.f, 0.f, 0.f, 0.f};
; #pragma unroll
;                 for (int i = 0; i < 4; ++i) {
;                     const float lw = -0.6065306597126334f * sigmoidf_(aw[i] + w0s);
;                     G = __builtin_amdgcn_mfma_f32_16x16x4f32((4 * fq + i <= fr) ? 1.f : 0.f, lw, G, 0, 0, 0);
;                 }
; #pragma unroll
;                 for (int i = 0; i < 4; ++i) {
;                     sWb[(mt * 16 + 4 * fq + i) * ck::SWLD + nt * 16 + fr] = G[i];
;                     sAb[(mt * 16 + 4 * fq + i) * ck::SWLD + nt * 16 + fr] = sigmoidf_(aa[i] + a0s);
;                 }
;             }
;             loadm(blk + 1);
;         };
	v_fma_f32 v192, v192, s98, v127
	v_fma_f32 v193, v193, s98, v127
	v_fma_f32 v194, v194, s98, v127
	v_fma_f32 v195, v195, s98, v127
	v_exp_f32_e32 v144, v144
	v_mfma_f32_16x16x4_f32 v[208:211], v104, v147, v[208:211]
	v_exp_f32_e32 v148, v148
	v_exp_f32_e32 v152, v152
	v_exp_f32_e32 v156, v156
	v_exp_f32_e32 v192, v192
	v_exp_f32_e32 v193, v193
	v_exp_f32_e32 v194, v194
	v_exp_f32_e32 v195, v195
	v_add_f32_e32 v144, 1.0, v144
	v_add_f32_e32 v148, 1.0, v148
	v_mfma_f32_16x16x4_f32 v[212:215], v104, v151, v[212:215]
	v_add_f32_e32 v152, 1.0, v152
	v_add_f32_e32 v156, 1.0, v156
	v_add_f32_e32 v192, 1.0, v192
	v_add_f32_e32 v193, 1.0, v193
	v_add_f32_e32 v194, 1.0, v194
	v_add_f32_e32 v195, 1.0, v195
	v_rcp_f32_e32 v144, v144
	v_rcp_f32_e32 v148, v148
	v_rcp_f32_e32 v152, v152
	v_mfma_f32_16x16x4_f32 v[182:185], v104, v155, v[182:185]
	v_rcp_f32_e32 v156, v156
	v_rcp_f32_e32 v192, v192
	v_rcp_f32_e32 v193, v193
	v_rcp_f32_e32 v194, v194
	v_rcp_f32_e32 v195, v195
	v_mul_f32_e32 v144, 0xbf1b4598, v144
	v_mul_f32_e32 v148, 0xbf1b4598, v148
	v_mul_f32_e32 v152, 0xbf1b4598, v152
	v_mul_f32_e32 v156, 0xbf1b4598, v156
	v_mfma_f32_16x16x4_f32 v[204:207], v105, v144, v[204:207]
	v_fma_f32 v145, v145, s98, v122
	v_fma_f32 v149, v149, s98, v123
	v_fma_f32 v153, v153, s98, v124
	v_fma_f32 v157, v157, s98, v125
	v_fma_f32 v196, v196, s98, v158
	v_fma_f32 v197, v197, s98, v158
	v_fma_f32 v198, v198, s98, v158
	v_fma_f32 v199, v199, s98, v158
	v_exp_f32_e32 v145, v145
	v_mfma_f32_16x16x4_f32 v[208:211], v105, v148, v[208:211]
	v_exp_f32_e32 v149, v149
	v_exp_f32_e32 v153, v153
	v_exp_f32_e32 v157, v157
	v_exp_f32_e32 v196, v196
	v_exp_f32_e32 v197, v197
	v_exp_f32_e32 v198, v198
	v_exp_f32_e32 v199, v199
	v_add_f32_e32 v145, 1.0, v145
	v_add_f32_e32 v149, 1.0, v149
	v_mfma_f32_16x16x4_f32 v[212:215], v105, v152, v[212:215]
	v_add_f32_e32 v153, 1.0, v153
	v_add_f32_e32 v157, 1.0, v157
	v_add_f32_e32 v196, 1.0, v196
	v_add_f32_e32 v197, 1.0, v197
	v_add_f32_e32 v198, 1.0, v198
	v_add_f32_e32 v199, 1.0, v199
	v_rcp_f32_e32 v145, v145
	v_rcp_f32_e32 v149, v149
	v_rcp_f32_e32 v153, v153
	v_mfma_f32_16x16x4_f32 v[182:185], v105, v156, v[182:185]
	v_rcp_f32_e32 v157, v157
	v_rcp_f32_e32 v196, v196
	v_rcp_f32_e32 v197, v197
	v_rcp_f32_e32 v198, v198
	v_rcp_f32_e32 v199, v199
	v_mul_f32_e32 v145, 0xbf1b4598, v145
	v_mul_f32_e32 v149, 0xbf1b4598, v149
	v_mul_f32_e32 v153, 0xbf1b4598, v153
	v_mul_f32_e32 v157, 0xbf1b4598, v157
	v_mfma_f32_16x16x4_f32 v[204:207], v106, v145, v[204:207]
	v_fma_f32 v200, v200, s98, v159
	v_fma_f32 v201, v201, s98, v159
	v_fma_f32 v202, v202, s98, v159
	v_fma_f32 v203, v203, s98, v159
	v_mfma_f32_16x16x4_f32 v[208:211], v106, v149, v[208:211]
	v_exp_f32_e32 v200, v200
	v_exp_f32_e32 v201, v201
	v_exp_f32_e32 v202, v202
	v_exp_f32_e32 v203, v203
	v_mfma_f32_16x16x4_f32 v[212:215], v106, v153, v[212:215]
	v_add_f32_e32 v200, 1.0, v200
	v_add_f32_e32 v201, 1.0, v201
	v_add_f32_e32 v202, 1.0, v202
	v_add_f32_e32 v203, 1.0, v203
	v_mfma_f32_16x16x4_f32 v[182:185], v106, v157, v[182:185]
	v_rcp_f32_e32 v200, v200
	v_rcp_f32_e32 v201, v201
	v_rcp_f32_e32 v202, v202
	v_rcp_f32_e32 v203, v203
	v_add_u32_e32 v141, s4, v107
	v_add_u32_e32 v129, s4, v121
	v_add_u32_e32 v160, s4, v108
	v_add_u32_e32 v161, s4, v109
	v_add_u32_e32 v186, s4, v110
	v_add_u32_e32 v187, s5, v107
	v_add_u32_e32 v122, s5, v121
	v_add_u32_e32 v123, s5, v108
	v_add_u32_e32 v124, s5, v109
	v_add_u32_e32 v125, s5, v110
	ds_write_b32 v141, v188
	ds_write2_b32 v129, v189, v190 offset0:68 offset1:136
	ds_write2_b32 v129, v191, v192 offset0:204 offset1:16
	ds_write2_b32 v129, v196, v200 offset0:32 offset1:48
	ds_write2_b32 v160, v193, v194 offset0:68 offset1:136
	ds_write_b32 v160, v195 offset:816
	ds_write2_b32 v161, v197, v198 offset0:68 offset1:136
	ds_write_b32 v161, v199 offset:816
	ds_write2_b32 v186, v201, v202 offset0:68 offset1:136
	ds_write_b32 v186, v203 offset:816
	ds_write2_b32 v187, v204, v208 offset1:16
	ds_write2_b32 v187, v212, v182 offset0:32 offset1:48
	ds_write2_b32 v122, v205, v206 offset0:68 offset1:136
	ds_write_b32 v122, v207 offset:816
	ds_write2_b32 v123, v209, v210 offset0:68 offset1:136
	ds_write_b32 v123, v211 offset:816
	ds_write2_b32 v124, v213, v214 offset0:68 offset1:136
	ds_write_b32 v124, v215 offset:816
	ds_write2_b32 v125, v183, v184 offset0:68 offset1:136
	ds_write_b32 v125, v185 offset:816
	s_branch .LBB0_685
	s_and_b64 vcc, exec, s[34:35]
	s_cbranch_vccnz .LBB0_695
	s_lshl_b32 s4, s22, 5
	v_add3_u32 v66, s4, 64, v116
	v_add_u32_e32 v68, s7, v118
	s_movk_i32 s4, 0xff
	v_or_b32_e32 v67, v66, v1
	v_cmp_lt_u32_e32 vcc, s4, v68
	s_and_saveexec_b64 s[4:5], vcc
	s_xor_b64 s[4:5], exec, s[4:5]
	v_sub_u32_e32 v66, 0x21ff, v67
	s_andn2_saveexec_b64 s[4:5], s[4:5]
	s_cbranch_execz .LBB0_683
	v_sub_u32_e32 v66, 0xff, v67
	s_branch .LBB0_683

; __device__ __forceinline__ f32x4 unpk4(u32x2 v) { return (f32x4){bflo(v.x), bfhi(v.x), bflo(v.y), bfhi(v.y)}; }
; __device__ __forceinline__ u32x2 pk4(f32x4 v) { u32x2 r; r.x = pk2(v[0], v[1]); r.y = pk2(v[2], v[3]); return r; }
; __device__ __forceinline__ float sigmoidf_(float x) { return rcpf_(1.f + __expf(-x)); }
; __device__ __forceinline__ float gelu_tanh(float x) { const float u = 1.5957691216057308f * (x + 0.044715f * x * x * x); return x * rcpf_(1.f + __expf(-u)); }
; __device__ __forceinline__ void phase_s5post(const PP& p, int l, int gw, int nw) {
;     ...
;             for (int nt = 0; nt < 16; ++nt) {
;                 f32x4 a = (f32x4){0.f, 0.f, 0.f, 0.f};
;                 const bf16_t* wp = GLU + (size_t)(nt * 16 + fr) * 256 + fq * 8;
; #pragma unroll
;                 for (int ks = 0; ks < 8; ++ks) a = __builtin_amdgcn_mfma_f32_16x16x32_bf16(*(const bf16x8*)(wp + ks * 32), yf[ks], a, 0, 0, 0);
;                 const int ch = nt * 16 + fq * 4, hh = ch & 15;
;                 const u32x2 y0 = *(const u32x2*)(Y5 + (size_t)(nt * 2) * GS5 + (size_t)R * 512 + t * 16 + hh), y1 = *(const u32x2*)(Y5 + (size_t)(nt * 2 + 1) * GS5 + (size_t)R * 512 + t * 16 + hh);
;                 const u32x2 uu = *(const u32x2*)(A2 + ((size_t)(nt * 2) * GROWS + R) * 640 + t * 16 + hh);
;                 const f32x4 dv = *(const f32x4*)(p.in[I_S5D] + l * 256 + ch), gb = *(const f32x4*)(p.in[I_GLUB] + l * 256 + ch);
;                 const f32x4 ys = unpk4(y0) + unpk4(y1) + dv * unpk4(uu);
;                 f32x4 o;
; #pragma unroll
;                 for (int i = 0; i < 4; ++i) { const float yy = gelu_tanh(ys[i]); o[i] = yy * sigmoidf_(a[i] + gb[i]); }
;                 *(u32x2*)(Y5w + (size_t)(nt * 2) * GS5 + (size_t)R * 512 + t * 16 + hh) = pk4(o);
;                 asm volatile("" ::: "memory");
;             }
.LBB0_885:
	v_lshl_add_u64 v[38:39], s[14:15], 0, v[36:37]
	v_add_co_u32_e32 v46, vcc, 0x1948000, v38
	s_mov_b32 s6, 0x1c54c000
	s_nop 0
	v_addc_co_u32_e32 v47, vcc, 0, v39, vcc
	global_load_dwordx4 v[216:219], v[46:47], off
	global_load_dwordx4 v[220:223], v[46:47], off offset:64
	global_load_dwordx4 v[224:227], v[46:47], off offset:128
	global_load_dwordx4 v[228:231], v[46:47], off offset:192
	global_load_dwordx4 v[232:235], v[46:47], off offset:256
	global_load_dwordx4 v[236:239], v[46:47], off offset:320
	global_load_dwordx4 v[240:243], v[46:47], off offset:384
	global_load_dwordx4 v[244:247], v[46:47], off offset:448
	v_mov_b32_e32 v46, s12
	ds_read_b64 v[46:47], v46
	v_lshl_add_u64 v[42:43], s[14:15], 0, v[112:113]
	v_add_co_u32_e32 v114, vcc, s6, v42
	s_mov_b32 s6, 0x1c654000
	s_nop 0
	v_addc_co_u32_e32 v115, vcc, 0, v43, vcc
	v_add_co_u32_e32 v42, vcc, s6, v42
	global_load_dwordx2 v[116:117], v[114:115], off
	s_nop 0
	v_addc_co_u32_e32 v43, vcc, 0, v43, vcc
	global_load_dwordx2 v[118:119], v[42:43], off
	v_lshl_add_u64 v[42:43], s[14:15], 0, v[34:35]
	global_load_dwordx2 v[122:123], v[42:43], off
	v_mov_b32_e32 v42, s41
	ds_read_b64 v[42:43], v42
	s_waitcnt lgkmcnt(0)
	v_readfirstlane_b32 s7, v43
	v_readfirstlane_b32 s6, v42
	s_nop 1
	v_lshl_add_u64 v[42:43], s[6:7], 0, v[106:107]
	v_readfirstlane_b32 s7, v47
	v_readfirstlane_b32 s6, v46
	v_lshl_add_u64 v[42:43], v[42:43], 0, s[4:5]
	global_load_dwordx4 v[42:45], v[42:43], off
	v_lshl_add_u64 v[46:47], s[6:7], 0, v[106:107]
	v_lshl_add_u64 v[46:47], v[46:47], 0, s[4:5]
	global_load_dwordx4 v[46:49], v[46:47], off
	s_waitcnt vmcnt(12)
	v_mfma_f32_16x16x32_bf16 v[38:41], v[216:219], v[2:5], 0
	s_waitcnt vmcnt(11)
	v_mfma_f32_16x16x32_bf16 v[38:41], v[220:223], v[6:9], v[38:41]
	s_waitcnt vmcnt(10)
	v_mfma_f32_16x16x32_bf16 v[38:41], v[224:227], v[10:13], v[38:41]
	s_waitcnt vmcnt(9)
	v_mfma_f32_16x16x32_bf16 v[38:41], v[228:231], v[14:17], v[38:41]
	s_waitcnt vmcnt(8)
	v_mfma_f32_16x16x32_bf16 v[38:41], v[232:235], v[18:21], v[38:41]
	s_waitcnt vmcnt(7)
	v_mfma_f32_16x16x32_bf16 v[38:41], v[236:239], v[22:25], v[38:41]
	s_waitcnt vmcnt(6)
	v_mfma_f32_16x16x32_bf16 v[38:41], v[240:243], v[26:29], v[38:41]
	s_waitcnt vmcnt(5)
	v_mfma_f32_16x16x32_bf16 v[38:41], v[244:247], v[30:33], v[38:41]
	s_waitcnt vmcnt(4)
	v_lshlrev_b32_e32 v124, 16, v116
	v_and_b32_e32 v125, 0xffff0000, v116
	v_lshlrev_b32_e32 v116, 16, v117
	v_and_b32_e32 v117, 0xffff0000, v117
	s_waitcnt vmcnt(3)
	v_lshlrev_b32_e32 v126, 16, v118
	v_and_b32_e32 v127, 0xffff0000, v118
	v_lshlrev_b32_e32 v118, 16, v119
	v_and_b32_e32 v119, 0xffff0000, v119
	v_pk_add_f32 v[116:117], v[116:117], v[118:119]
	v_pk_add_f32 v[118:119], v[124:125], v[126:127]
	s_mov_b64 s[6:7], 0x210000
	s_add_u32 s4, s4, 64
	v_lshl_add_u64 v[112:113], v[112:113], 0, s[6:7]
	s_mov_b64 s[6:7], 0x294000
	s_addc_u32 s5, s5, 0
	v_lshl_add_u64 v[34:35], v[34:35], 0, s[6:7]
	s_mov_b64 s[6:7], 0x2000
	v_lshl_add_u64 v[36:37], v[36:37], 0, s[6:7]
	s_cmpk_eq_i32 s4, 0x400
	s_waitcnt vmcnt(0)
	v_add_f32_e32 v38, v38, v46
	v_add_f32_e32 v39, v39, v47
	v_lshlrev_b32_e32 v46, 16, v122
	v_and_b32_e32 v47, 0xffff0000, v122
	v_pk_fma_f32 v[42:43], v[42:43], v[46:47], v[118:119]
	v_mul_f32_e32 v38, 0xbfb8aa3b, v38
	v_mul_f32_e32 v46, 0x3d372713, v42
	v_mul_f32_e32 v47, 0x3d372713, v43
	v_mul_f32_e32 v46, v42, v46
	v_mul_f32_e32 v47, v43, v47
	v_fma_f32 v46, v42, v46, v42
	v_fma_f32 v47, v43, v47, v43
	v_mul_f32_e32 v46, 0xbfcc422a, v46
	v_mul_f32_e32 v47, 0xbfcc422a, v47
	v_mul_f32_e32 v46, 0x3fb8aa3b, v46
	v_mul_f32_e32 v47, 0x3fb8aa3b, v47
	v_mul_f32_e32 v39, 0xbfb8aa3b, v39
	v_exp_f32_e32 v46, v46
	v_exp_f32_e32 v47, v47
	v_exp_f32_e32 v38, v38
	v_exp_f32_e32 v39, v39
	v_add_f32_e32 v46, 1.0, v46
	v_add_f32_e32 v47, 1.0, v47
	v_add_f32_e32 v38, 1.0, v38
	v_add_f32_e32 v39, 1.0, v39
	v_rcp_f32_e32 v46, v46
	v_rcp_f32_e32 v47, v47
	v_rcp_f32_e32 v38, v38
	v_rcp_f32_e32 v39, v39
	v_add_f32_e32 v40, v40, v48
	v_pk_mul_f32 v[42:43], v[42:43], v[46:47]
	v_add_f32_e32 v41, v41, v49
	v_pk_mul_f32 v[38:39], v[38:39], v[42:43]
	v_lshlrev_b32_e32 v42, 16, v123
	v_and_b32_e32 v43, 0xffff0000, v123
	v_pk_fma_f32 v[42:43], v[44:45], v[42:43], v[116:117]
	v_mul_f32_e32 v40, 0xbfb8aa3b, v40
	v_mul_f32_e32 v44, 0x3d372713, v42
	v_mul_f32_e32 v45, 0x3d372713, v43
	v_mul_f32_e32 v44, v42, v44
	v_mul_f32_e32 v45, v43, v45
	v_fma_f32 v44, v42, v44, v42
	v_fma_f32 v45, v43, v45, v43
	v_mul_f32_e32 v44, 0xbfcc422a, v44
	v_mul_f32_e32 v45, 0xbfcc422a, v45
	v_mul_f32_e32 v44, 0x3fb8aa3b, v44
	v_mul_f32_e32 v45, 0x3fb8aa3b, v45
	v_mul_f32_e32 v41, 0xbfb8aa3b, v41
	v_exp_f32_e32 v44, v44
	v_exp_f32_e32 v45, v45
	v_exp_f32_e32 v40, v40
	v_exp_f32_e32 v41, v41
	v_add_f32_e32 v44, 1.0, v44
	v_add_f32_e32 v45, 1.0, v45
	v_add_f32_e32 v40, 1.0, v40
	v_add_f32_e32 v41, 1.0, v41
	v_rcp_f32_e32 v44, v44
	v_rcp_f32_e32 v45, v45
	v_rcp_f32_e32 v40, v40
	v_rcp_f32_e32 v41, v41
	v_cvt_pk_bf16_f32 v38, v38, v39
	v_pk_mul_f32 v[42:43], v[42:43], v[44:45]
	s_nop 0
	v_pk_mul_f32 v[40:41], v[40:41], v[42:43]
	s_nop 0
	v_cvt_pk_bf16_f32 v39, v40, v41
	global_store_dwordx2 v[114:115], v[38:39], off
	s_cbranch_scc0 .LBB0_885
	v_readlane_b32 s4, v253, 47
	s_nop 1
	v_add_u32_e32 v101, s4, v101
	s_movk_i32 s4, 0x83f
	v_cmp_lt_i32_e32 vcc, s4, v101
	s_or_b64 s[34:35], vcc, s[34:35]
	s_andn2_b64 exec, exec, s[34:35]
	s_cbranch_execnz .LBB0_884

; __device__ __forceinline__ u32x2 pk4(f32x4 v) { u32x2 r; r.x = pk2(v[0], v[1]); r.y = pk2(v[2], v[3]); return r; }
; __device__ __forceinline__ void phase_gaterw(const PP& p, int l, int gw, int nw) {
;     ...
; #pragma unroll 4
;         for (int n24 = 0; n24 < 24; ++n24) {
;             f32x4 ga = (f32x4){0.f, 0.f, 0.f, 0.f};
;             const bf16_t* wp = GUP + (size_t)(n24 * 16 + fr) * 128 + fq * 8;
; #pragma unroll
;             for (int ks = 0; ks < 4; ++ks) ga = __builtin_amdgcn_mfma_f32_16x16x32_bf16(*(const bf16x8*)(wp + ks * 32), gfrag[ks], ga, 0, 0, 0);
;             *(u32x2*)(gr + n24 * 16 + fq * 4) = pk4(ga);
;         }
.LBB0_922:
	v_lshl_add_u64 v[24:25], s[14:15], 0, v[20:21]
	v_add_co_u32_e32 v22, vcc, 0x1930000, v24
	s_mov_b32 s7, 0x1931000
	s_nop 0
	v_addc_co_u32_e32 v23, vcc, 0, v25, vcc
	v_add_co_u32_e32 v50, vcc, s7, v24
	s_mov_b32 s7, 0x1932000
	s_nop 0
	v_addc_co_u32_e32 v51, vcc, 0, v25, vcc
	global_load_dwordx4 v[216:219], v[22:23], off
	global_load_dwordx4 v[220:223], v[22:23], off offset:64
	global_load_dwordx4 v[224:227], v[22:23], off offset:128
	global_load_dwordx4 v[228:231], v[22:23], off offset:192
	global_load_dwordx4 v[232:235], v[50:51], off
	global_load_dwordx4 v[236:239], v[50:51], off offset:64
	global_load_dwordx4 v[240:243], v[50:51], off offset:128
	global_load_dwordx4 v[244:247], v[50:51], off offset:192
	v_add_co_u32_e32 v52, vcc, s7, v24
	s_mov_b32 s7, 0x1933000
	s_nop 0
	v_addc_co_u32_e32 v53, vcc, 0, v25, vcc
	v_add_co_u32_e32 v24, vcc, s7, v24
	s_add_i32 s6, s6, -4
	s_nop 0
	v_addc_co_u32_e32 v25, vcc, 0, v25, vcc
	s_mov_b64 s[22:23], 0x4000
	v_lshl_add_u64 v[20:21], v[20:21], 0, s[22:23]
	v_lshl_add_u64 v[22:23], s[14:15], 0, v[18:19]
	v_lshl_add_u64 v[18:19], v[18:19], 0, s[2:3]
	s_waitcnt vmcnt(7)
	v_mfma_f32_16x16x32_bf16 v[42:45], v[216:219], v[10:13], 0
	s_waitcnt vmcnt(6)
	v_mfma_f32_16x16x32_bf16 v[42:45], v[220:223], v[6:9], v[42:45]
	s_waitcnt vmcnt(5)
	v_mfma_f32_16x16x32_bf16 v[42:45], v[224:227], v[2:5], v[42:45]
	s_waitcnt vmcnt(4)
	v_mfma_f32_16x16x32_bf16 v[42:45], v[228:231], v[14:17], v[42:45]
	global_load_dwordx4 v[216:219], v[52:53], off
	global_load_dwordx4 v[220:223], v[52:53], off offset:64
	global_load_dwordx4 v[224:227], v[52:53], off offset:128
	global_load_dwordx4 v[228:231], v[52:53], off offset:192
	s_waitcnt vmcnt(7)
	v_mfma_f32_16x16x32_bf16 v[46:49], v[232:235], v[10:13], 0
	s_waitcnt vmcnt(6)
	v_mfma_f32_16x16x32_bf16 v[46:49], v[236:239], v[6:9], v[46:49]
	s_waitcnt vmcnt(5)
	v_mfma_f32_16x16x32_bf16 v[46:49], v[240:243], v[2:5], v[46:49]
	s_waitcnt vmcnt(4)
	v_mfma_f32_16x16x32_bf16 v[46:49], v[244:247], v[14:17], v[46:49]
	global_load_dwordx4 v[232:235], v[24:25], off
	global_load_dwordx4 v[236:239], v[24:25], off offset:64
	global_load_dwordx4 v[240:243], v[24:25], off offset:128
	global_load_dwordx4 v[244:247], v[24:25], off offset:192
	s_waitcnt vmcnt(7)
	v_mfma_f32_16x16x32_bf16 v[248:251], v[216:219], v[10:13], 0
	s_waitcnt vmcnt(6)
	v_mfma_f32_16x16x32_bf16 v[248:251], v[220:223], v[6:9], v[248:251]
	s_waitcnt vmcnt(5)
	v_mfma_f32_16x16x32_bf16 v[248:251], v[224:227], v[2:5], v[248:251]
	s_waitcnt vmcnt(4)
	v_mfma_f32_16x16x32_bf16 v[248:251], v[228:231], v[14:17], v[248:251]
	s_waitcnt vmcnt(3)
	v_mfma_f32_16x16x32_bf16 v[50:53], v[232:235], v[10:13], 0
	s_waitcnt vmcnt(2)
	v_mfma_f32_16x16x32_bf16 v[50:53], v[236:239], v[6:9], v[50:53]
	s_waitcnt vmcnt(1)
	v_mfma_f32_16x16x32_bf16 v[50:53], v[240:243], v[2:5], v[50:53]
	s_waitcnt vmcnt(0)
	v_mfma_f32_16x16x32_bf16 v[50:53], v[244:247], v[14:17], v[50:53]
	v_cvt_pk_bf16_f32 v42, v42, v43
	v_cvt_pk_bf16_f32 v43, v44, v45
	global_store_dwordx2 v[22:23], v[42:43], off
	v_cvt_pk_bf16_f32 v46, v46, v47
	v_cvt_pk_bf16_f32 v47, v48, v49
	global_store_dwordx2 v[22:23], v[46:47], off offset:32
	v_cvt_pk_bf16_f32 v248, v248, v249
	v_cvt_pk_bf16_f32 v249, v250, v251
	global_store_dwordx2 v[22:23], v[248:249], off offset:64
	v_cvt_pk_bf16_f32 v24, v50, v51
	v_cvt_pk_bf16_f32 v25, v52, v53
	global_store_dwordx2 v[22:23], v[24:25], off offset:96
	s_cmp_eq_u32 s6, 0
	s_cbranch_scc0 .LBB0_922
	v_readlane_b32 s6, v253, 47
	s_nop 1
	v_add_u32_e32 v41, s6, v41
	s_movk_i32 s6, 0x83f
	v_cmp_lt_i32_e32 vcc, s6, v41
	s_or_b64 s[4:5], vcc, s[4:5]
	s_andn2_b64 exec, exec, s[4:5]
	s_cbranch_execnz .LBB0_889
